# v87: every workgroup issues buffer_wbl2 sc1 right after its barrier-arrival atomic (7 sites) so the last arriver's release flush has less dirty L2 to write back
# baseline (speedup 1.0000x reference)
.LBB0_266:
	s_mov_b64 s[8:9], exec
	v_mbcnt_lo_u32_b32 v0, s8, 0
	v_mbcnt_hi_u32_b32 v0, s9, v0
	v_cmp_eq_u32_e32 vcc, 0, v0
	s_and_saveexec_b64 s[6:7], vcc
	s_cbranch_execz .LBB0_268
	s_bcnt1_i32_b64 s8, s[8:9]
	v_mov_b32_e32 v4, s8
	v_readlane_b32 s8, v254, 5
	v_readlane_b32 s9, v254, 6
	s_nop 4
	global_atomic_add v4, v1, v4, s[8:9] sc0
	buffer_wbl2 sc1
